# RWKV scanner loop hand-rewritten: LDS reads software-pipelined one step ahead, no nops, same f32 math (bit-exact)
# speedup vs baseline: 1.0098x; 1.0098x over previous
.LBB0_587:
	v_lshrrev_b32_e32 v2, 4, v52
	v_and_b32_e32 v2, 3, v2
	v_lshrrev_b32_e32 v3, 2, v52
	v_and_or_b32 v3, v3, 48, v4
	v_readlane_b32 s0, v254, 14
	v_mul_u32_u24_e32 v7, 0x110, v4
	v_lshlrev_b32_e32 v8, 4, v2
	v_readlane_b32 s1, v254, 15
	v_lshl_add_u32 v89, v0, 2, s0
	v_readlane_b32 s0, v254, 13
	v_add3_u32 v133, s1, v7, v8
	v_mul_u32_u24_e32 v7, 0x110, v3
	v_add3_u32 v134, s0, v7, v8
	s_lshl_b32 s0, s8, 4
	v_and_b32_e32 v6, 4, v52
	s_add_u32 s8, s2, s0
	v_lshlrev_b32_e32 v1, 2, v1
	v_cmp_eq_u32_e64 s[44:45], 0, v6
	v_and_b32_e32 v6, 2, v52
	v_cmp_eq_u32_e64 s[50:51], 0, v4
	v_lshlrev_b32_e32 v135, 4, v0
	v_mul_u32_u24_e32 v4, 0x110, v0
	s_addc_u32 s9, s3, 0
	v_lshl_or_b32 v0, v0, 8, v1
	s_lshl_b32 s4, s18, 1
	v_cmp_eq_u32_e64 s[46:47], 0, v6
	v_and_b32_e32 v6, 1, v52
	v_lshlrev_b32_e32 v7, 1, v88
	v_add_u32_e32 v132, 0, v0
	s_add_u32 s0, s34, s4
	v_lshlrev_b32_e32 v0, 7, v52
	v_and_b32_e32 v5, 7, v52
	v_add3_u32 v136, s1, v4, v7
	v_and_b32_e32 v4, 0xf8, v52
	s_addc_u32 s1, s35, 0
	v_and_b32_e32 v0, 0x300, v0
	v_lshlrev_b32_e32 v1, 2, v6
	v_cmp_eq_u32_e64 s[42:43], 0, v5
	v_lshlrev_b32_e32 v5, 5, v5
	v_lshlrev_b32_e32 v2, 10, v2
	v_lshlrev_b32_e32 v3, 2, v3
	v_lshl_add_u64 v[110:111], s[0:1], 0, v[30:31]
	v_or3_b32 v0, v0, v4, v1
	v_readlane_b32 s0, v254, 16
	v_cmp_eq_u32_e64 s[48:49], 0, v6
	v_add_u32_e32 v137, 0, v4
	v_add3_u32 v138, 0, v2, v3
	v_add_u32_e32 v139, 0xf200, v0
	v_or_b32_e32 v140, 0xd200, v4
	v_or_b32_e32 v141, 0x8200, v5
	v_add_u32_e32 v142, s0, v0
	v_add_u32_e32 v143, 0, v5
	v_mov_b32_e32 v0, v31
	v_mov_b32_e32 v1, v31
	v_mov_b32_e32 v2, v31
	v_mov_b32_e32 v3, v31
	v_mov_b32_e32 v4, v31
	v_mov_b32_e32 v5, v31
	v_mov_b32_e32 v6, v31
	v_mov_b32_e32 v7, v31
	v_mov_b32_e32 v144, 0
	s_mov_b32 s2, -1
	v_mov_b32_e32 v167, 0
	v_mov_b32_e32 v166, 0
	v_mov_b32_e32 v165, 0
	v_mov_b32_e32 v164, 0
	v_mov_b32_e32 v147, 0
	v_mov_b32_e32 v146, 0
	v_mov_b32_e32 v145, 0
	v_readlane_b32 s18, v251, 55
	v_readlane_b32 s19, v251, 56
	s_and_b64 vcc, exec, s[18:19]
	s_cbranch_vccnz .Lscan_entry
	s_branch .LBB0_590
.Lscan_entry:
	s_waitcnt vmcnt(0) lgkmcnt(0)
	v_and_b32_e32 v140, 7, v161
	v_lshrrev_b32_e32 v141, 3, v161
	v_lshlrev_b32_e32 v137, 5, v140
	v_lshlrev_b32_e32 v139, 3, v141
	v_lshrrev_b32_e32 v142, 1, v140
	v_and_b32_e32 v143, 1, v140
	v_lshlrev_b32_e32 v142, 8, v142
	v_lshlrev_b32_e32 v143, 2, v143
	v_add3_u32 v84, v139, v142, v143
	v_add_u32_e32 v84, 0x7000, v84
	v_add_u32_e32 v139, 0x5000, v139
	v_mov_b32_e32 v156, 0x8000
	v_cndmask_b32_e64 v128, 0, 1.0, s[42:43]
	v_cndmask_b32_e64 v129, 0, 1.0, s[42:43]
	v_mov_b32_e32 v0, 0
	v_mov_b32_e32 v1, 0
	v_mov_b32_e32 v2, 0
	v_mov_b32_e32 v3, 0
	v_mov_b32_e32 v4, 0
	v_mov_b32_e32 v5, 0
	v_mov_b32_e32 v6, 0
	v_mov_b32_e32 v7, 0
	v_mov_b32_e32 v8, 0
	v_mov_b32_e32 v9, 0
	v_mov_b32_e32 v10, 0
	v_mov_b32_e32 v11, 0
	v_mov_b32_e32 v12, 0
	v_mov_b32_e32 v13, 0
	v_mov_b32_e32 v14, 0
	v_mov_b32_e32 v15, 0
	s_mov_b32 s1, 0
	s_movk_i32 s2, 0x80
	s_barrier
.Lscan_chunk:
	v_add_u32_e32 v130, s1, v137
	v_add_u32_e32 v131, s1, v139
	v_add_u32_e32 v85, s1, v156
	v_add_u32_e32 v86, s1, v84
	s_mov_b32 s0, 4
	ds_read_b128 v[32:35], v130 offset:0
	ds_read_b128 v[36:39], v130 offset:16
	ds_read_b128 v[40:43], v130 offset:4096
	ds_read_b128 v[44:47], v130 offset:4112
	ds_read_b128 v[56:59], v130 offset:12288
	ds_read_b128 v[60:63], v130 offset:12304
	ds_read_b128 v[64:67], v130 offset:16384
	ds_read_b128 v[68:71], v130 offset:16400
	ds_read_b64 v[72:73], v131 offset:0
	ds_read_b128 v[48:51], v130 offset:8192
	ds_read_b128 v[52:55], v130 offset:8208
	ds_read_b64 v[74:75], v85 offset:0
.Lscan_q4:
	s_waitcnt lgkmcnt(0)
	v_pk_mul_f32 v[16:17], v[2:3], v[34:35]
	v_pk_mul_f32 v[18:19], v[10:11], v[34:35]
	ds_read_b128 v[76:79], v130 offset:256
	v_pk_fma_f32 v[16:17], v[0:1], v[32:33], v[16:17]
	v_pk_fma_f32 v[18:19], v[8:9], v[32:33], v[18:19]
	ds_read_b128 v[80:83], v130 offset:272
	v_pk_fma_f32 v[16:17], v[4:5], v[36:37], v[16:17]
	v_pk_fma_f32 v[18:19], v[12:13], v[36:37], v[18:19]
	ds_read_b128 v[90:93], v130 offset:4352
	v_pk_fma_f32 v[16:17], v[6:7], v[38:39], v[16:17]
	v_pk_fma_f32 v[18:19], v[14:15], v[38:39], v[18:19]
	ds_read_b128 v[94:97], v130 offset:4368
	v_pk_mul_f32 v[20:21], v[2:3], v[42:43]
	v_add_f32_e32 v24, v16, v17
	ds_read_b128 v[112:115], v130 offset:12544
	v_add_f32_e32 v25, v18, v19
	v_pk_mul_f32 v[22:23], v[10:11], v[42:43]
	ds_read_b128 v[116:119], v130 offset:12560
	v_add_f32_dpp v24, v24, v24 quad_perm:[1,0,3,2] row_mask:0xf bank_mask:0xf bound_ctrl:1
	v_add_f32_dpp v25, v25, v25 quad_perm:[1,0,3,2] row_mask:0xf bank_mask:0xf bound_ctrl:1
	ds_read_b128 v[120:123], v130 offset:16640
	v_pk_fma_f32 v[20:21], v[0:1], v[40:41], v[20:21]
	v_add_f32_dpp v24, v24, v24 quad_perm:[2,3,0,1] row_mask:0xf bank_mask:0xf bound_ctrl:1
	ds_read_b128 v[124:127], v130 offset:16656
	v_add_f32_dpp v25, v25, v25 quad_perm:[2,3,0,1] row_mask:0xf bank_mask:0xf bound_ctrl:1
	v_pk_fma_f32 v[22:23], v[8:9], v[40:41], v[22:23]
	ds_read_b64 v[106:107], v131 offset:256
	v_add_f32_dpp v24, v24, v24 row_half_mirror row_mask:0xf bank_mask:0xf bound_ctrl:1
	v_add_f32_dpp v25, v25, v25 row_half_mirror row_mask:0xf bank_mask:0xf bound_ctrl:1
	ds_read_b128 v[98:101], v130 offset:8448
	v_pk_fma_f32 v[20:21], v[4:5], v[44:45], v[20:21]
	v_pk_fma_f32 v[22:23], v[12:13], v[44:45], v[22:23]
	ds_read_b128 v[102:105], v130 offset:8464
	v_pk_fma_f32 v[20:21], v[6:7], v[46:47], v[20:21]
	v_pk_fma_f32 v[22:23], v[14:15], v[46:47], v[22:23]
	ds_read_b64 v[108:109], v85 offset:16
	v_pk_mul_f32 v[164:165], v[56:57], v[24:25] op_sel_hi:[1,0]
	v_pk_mul_f32 v[166:167], v[56:57], v[24:25] op_sel:[0,1]
	v_pk_mul_f32 v[168:169], v[58:59], v[24:25] op_sel_hi:[1,0]
	v_pk_mul_f32 v[170:171], v[58:59], v[24:25] op_sel:[0,1]
	v_pk_fma_f32 v[164:165], v[64:65], v[72:73], v[164:165] op_sel_hi:[1,0,1]
	v_pk_fma_f32 v[166:167], v[64:65], v[72:73], v[166:167] op_sel:[0,1,0]
	v_pk_fma_f32 v[168:169], v[66:67], v[72:73], v[168:169] op_sel_hi:[1,0,1]
	v_pk_fma_f32 v[170:171], v[66:67], v[72:73], v[170:171] op_sel:[0,1,0]
	v_pk_fma_f32 v[0:1], v[0:1], v[48:49], v[164:165]
	v_pk_fma_f32 v[8:9], v[8:9], v[48:49], v[166:167]
	v_pk_fma_f32 v[2:3], v[2:3], v[50:51], v[168:169]
	v_pk_fma_f32 v[10:11], v[10:11], v[50:51], v[170:171]
	v_pk_mul_f32 v[164:165], v[60:61], v[24:25] op_sel_hi:[1,0]
	v_pk_mul_f32 v[166:167], v[60:61], v[24:25] op_sel:[0,1]
	v_pk_mul_f32 v[168:169], v[62:63], v[24:25] op_sel_hi:[1,0]
	v_pk_mul_f32 v[170:171], v[62:63], v[24:25] op_sel:[0,1]
	v_pk_fma_f32 v[164:165], v[68:69], v[72:73], v[164:165] op_sel_hi:[1,0,1]
	v_pk_fma_f32 v[166:167], v[68:69], v[72:73], v[166:167] op_sel:[0,1,0]
	v_pk_fma_f32 v[168:169], v[70:71], v[72:73], v[168:169] op_sel_hi:[1,0,1]
	v_pk_fma_f32 v[170:171], v[70:71], v[72:73], v[170:171] op_sel:[0,1,0]
	v_pk_fma_f32 v[4:5], v[4:5], v[52:53], v[164:165]
	v_pk_fma_f32 v[12:13], v[12:13], v[52:53], v[166:167]
	v_pk_fma_f32 v[6:7], v[6:7], v[54:55], v[168:169]
	v_pk_fma_f32 v[14:15], v[14:15], v[54:55], v[170:171]
	v_pk_mul_f32 v[172:173], v[24:25], v[74:75] op_sel_hi:[1,0]
	v_pk_mul_f32 v[174:175], v[72:73], v[74:75] op_sel:[0,1]
	v_add_f32_e32 v26, v20, v21
	v_pk_add_f32 v[172:173], v[174:175], v[172:173]
	v_add_f32_e32 v27, v22, v23
	v_pk_fma_f32 v[176:177], v[172:173], v[128:129], v[26:27]
	s_waitcnt lgkmcnt(0)
	v_pk_mul_f32 v[16:17], v[2:3], v[78:79]
	v_pk_mul_f32 v[18:19], v[10:11], v[78:79]
	ds_read_b128 v[32:35], v130 offset:512
	v_pk_fma_f32 v[16:17], v[0:1], v[76:77], v[16:17]
	v_pk_fma_f32 v[18:19], v[8:9], v[76:77], v[18:19]
	ds_read_b128 v[36:39], v130 offset:528
	v_pk_fma_f32 v[16:17], v[4:5], v[80:81], v[16:17]
	v_pk_fma_f32 v[18:19], v[12:13], v[80:81], v[18:19]
	ds_read_b128 v[40:43], v130 offset:4608
	v_pk_fma_f32 v[16:17], v[6:7], v[82:83], v[16:17]
	v_pk_fma_f32 v[18:19], v[14:15], v[82:83], v[18:19]
	ds_read_b128 v[44:47], v130 offset:4624
	v_pk_mul_f32 v[20:21], v[2:3], v[92:93]
	v_add_f32_e32 v24, v16, v17
	ds_read_b128 v[56:59], v130 offset:12800
	v_add_f32_e32 v25, v18, v19
	v_pk_mul_f32 v[22:23], v[10:11], v[92:93]
	ds_read_b128 v[60:63], v130 offset:12816
	v_add_f32_dpp v24, v24, v24 quad_perm:[1,0,3,2] row_mask:0xf bank_mask:0xf bound_ctrl:1
	v_add_f32_dpp v25, v25, v25 quad_perm:[1,0,3,2] row_mask:0xf bank_mask:0xf bound_ctrl:1
	ds_read_b128 v[64:67], v130 offset:16896
	v_pk_fma_f32 v[20:21], v[0:1], v[90:91], v[20:21]
	v_add_f32_dpp v24, v24, v24 quad_perm:[2,3,0,1] row_mask:0xf bank_mask:0xf bound_ctrl:1
	ds_read_b128 v[68:71], v130 offset:16912
	v_add_f32_dpp v25, v25, v25 quad_perm:[2,3,0,1] row_mask:0xf bank_mask:0xf bound_ctrl:1
	v_pk_fma_f32 v[22:23], v[8:9], v[90:91], v[22:23]
	ds_read_b64 v[72:73], v131 offset:512
	v_add_f32_dpp v24, v24, v24 row_half_mirror row_mask:0xf bank_mask:0xf bound_ctrl:1
	v_add_f32_dpp v25, v25, v25 row_half_mirror row_mask:0xf bank_mask:0xf bound_ctrl:1
	ds_read_b128 v[48:51], v130 offset:8704
	v_pk_fma_f32 v[20:21], v[4:5], v[94:95], v[20:21]
	v_pk_fma_f32 v[22:23], v[12:13], v[94:95], v[22:23]
	ds_read_b128 v[52:55], v130 offset:8720
	v_pk_fma_f32 v[20:21], v[6:7], v[96:97], v[20:21]
	v_pk_fma_f32 v[22:23], v[14:15], v[96:97], v[22:23]
	ds_read_b64 v[74:75], v85 offset:32
	v_pk_mul_f32 v[164:165], v[112:113], v[24:25] op_sel_hi:[1,0]
	v_pk_mul_f32 v[166:167], v[112:113], v[24:25] op_sel:[0,1]
	v_pk_mul_f32 v[168:169], v[114:115], v[24:25] op_sel_hi:[1,0]
	v_pk_mul_f32 v[170:171], v[114:115], v[24:25] op_sel:[0,1]
	v_pk_fma_f32 v[164:165], v[120:121], v[106:107], v[164:165] op_sel_hi:[1,0,1]
	v_pk_fma_f32 v[166:167], v[120:121], v[106:107], v[166:167] op_sel:[0,1,0]
	v_pk_fma_f32 v[168:169], v[122:123], v[106:107], v[168:169] op_sel_hi:[1,0,1]
	v_pk_fma_f32 v[170:171], v[122:123], v[106:107], v[170:171] op_sel:[0,1,0]
	v_pk_fma_f32 v[0:1], v[0:1], v[98:99], v[164:165]
	v_pk_fma_f32 v[8:9], v[8:9], v[98:99], v[166:167]
	v_pk_fma_f32 v[2:3], v[2:3], v[100:101], v[168:169]
	v_pk_fma_f32 v[10:11], v[10:11], v[100:101], v[170:171]
	v_pk_mul_f32 v[164:165], v[116:117], v[24:25] op_sel_hi:[1,0]
	v_pk_mul_f32 v[166:167], v[116:117], v[24:25] op_sel:[0,1]
	v_pk_mul_f32 v[168:169], v[118:119], v[24:25] op_sel_hi:[1,0]
	v_pk_mul_f32 v[170:171], v[118:119], v[24:25] op_sel:[0,1]
	v_pk_fma_f32 v[164:165], v[124:125], v[106:107], v[164:165] op_sel_hi:[1,0,1]
	v_pk_fma_f32 v[166:167], v[124:125], v[106:107], v[166:167] op_sel:[0,1,0]
	v_pk_fma_f32 v[168:169], v[126:127], v[106:107], v[168:169] op_sel_hi:[1,0,1]
	v_pk_fma_f32 v[170:171], v[126:127], v[106:107], v[170:171] op_sel:[0,1,0]
	v_pk_fma_f32 v[4:5], v[4:5], v[102:103], v[164:165]
	v_pk_fma_f32 v[12:13], v[12:13], v[102:103], v[166:167]
	v_pk_fma_f32 v[6:7], v[6:7], v[104:105], v[168:169]
	v_pk_fma_f32 v[14:15], v[14:15], v[104:105], v[170:171]
	v_pk_mul_f32 v[172:173], v[24:25], v[108:109] op_sel_hi:[1,0]
	v_pk_mul_f32 v[174:175], v[106:107], v[108:109] op_sel:[0,1]
	v_add_f32_e32 v26, v20, v21
	v_pk_add_f32 v[172:173], v[174:175], v[172:173]
	v_add_f32_e32 v27, v22, v23
	v_pk_fma_f32 v[178:179], v[172:173], v[128:129], v[26:27]
	s_waitcnt lgkmcnt(0)
	v_pk_mul_f32 v[16:17], v[2:3], v[34:35]
	v_pk_mul_f32 v[18:19], v[10:11], v[34:35]
	ds_read_b128 v[76:79], v130 offset:768
	v_pk_fma_f32 v[16:17], v[0:1], v[32:33], v[16:17]
	v_pk_fma_f32 v[18:19], v[8:9], v[32:33], v[18:19]
	ds_read_b128 v[80:83], v130 offset:784
	v_pk_fma_f32 v[16:17], v[4:5], v[36:37], v[16:17]
	v_pk_fma_f32 v[18:19], v[12:13], v[36:37], v[18:19]
	ds_read_b128 v[90:93], v130 offset:4864
	v_pk_fma_f32 v[16:17], v[6:7], v[38:39], v[16:17]
	v_pk_fma_f32 v[18:19], v[14:15], v[38:39], v[18:19]
	ds_read_b128 v[94:97], v130 offset:4880
	v_pk_mul_f32 v[20:21], v[2:3], v[42:43]
	v_add_f32_e32 v24, v16, v17
	ds_read_b128 v[112:115], v130 offset:13056
	v_add_f32_e32 v25, v18, v19
	v_pk_mul_f32 v[22:23], v[10:11], v[42:43]
	ds_read_b128 v[116:119], v130 offset:13072
	v_add_f32_dpp v24, v24, v24 quad_perm:[1,0,3,2] row_mask:0xf bank_mask:0xf bound_ctrl:1
	v_add_f32_dpp v25, v25, v25 quad_perm:[1,0,3,2] row_mask:0xf bank_mask:0xf bound_ctrl:1
	ds_read_b128 v[120:123], v130 offset:17152
	v_pk_fma_f32 v[20:21], v[0:1], v[40:41], v[20:21]
	v_add_f32_dpp v24, v24, v24 quad_perm:[2,3,0,1] row_mask:0xf bank_mask:0xf bound_ctrl:1
	ds_read_b128 v[124:127], v130 offset:17168
	v_add_f32_dpp v25, v25, v25 quad_perm:[2,3,0,1] row_mask:0xf bank_mask:0xf bound_ctrl:1
	v_pk_fma_f32 v[22:23], v[8:9], v[40:41], v[22:23]
	ds_read_b64 v[106:107], v131 offset:768
	v_add_f32_dpp v24, v24, v24 row_half_mirror row_mask:0xf bank_mask:0xf bound_ctrl:1
	v_add_f32_dpp v25, v25, v25 row_half_mirror row_mask:0xf bank_mask:0xf bound_ctrl:1
	ds_read_b128 v[98:101], v130 offset:8960
	v_pk_fma_f32 v[20:21], v[4:5], v[44:45], v[20:21]
	v_pk_fma_f32 v[22:23], v[12:13], v[44:45], v[22:23]
	ds_read_b128 v[102:105], v130 offset:8976
	v_pk_fma_f32 v[20:21], v[6:7], v[46:47], v[20:21]
	v_pk_fma_f32 v[22:23], v[14:15], v[46:47], v[22:23]
	ds_read_b64 v[108:109], v85 offset:48
	v_pk_mul_f32 v[164:165], v[56:57], v[24:25] op_sel_hi:[1,0]
	v_pk_mul_f32 v[166:167], v[56:57], v[24:25] op_sel:[0,1]
	v_pk_mul_f32 v[168:169], v[58:59], v[24:25] op_sel_hi:[1,0]
	v_pk_mul_f32 v[170:171], v[58:59], v[24:25] op_sel:[0,1]
	v_pk_fma_f32 v[164:165], v[64:65], v[72:73], v[164:165] op_sel_hi:[1,0,1]
	v_pk_fma_f32 v[166:167], v[64:65], v[72:73], v[166:167] op_sel:[0,1,0]
	v_pk_fma_f32 v[168:169], v[66:67], v[72:73], v[168:169] op_sel_hi:[1,0,1]
	v_pk_fma_f32 v[170:171], v[66:67], v[72:73], v[170:171] op_sel:[0,1,0]
	v_pk_fma_f32 v[0:1], v[0:1], v[48:49], v[164:165]
	v_pk_fma_f32 v[8:9], v[8:9], v[48:49], v[166:167]
	v_pk_fma_f32 v[2:3], v[2:3], v[50:51], v[168:169]
	v_pk_fma_f32 v[10:11], v[10:11], v[50:51], v[170:171]
	v_pk_mul_f32 v[164:165], v[60:61], v[24:25] op_sel_hi:[1,0]
	v_pk_mul_f32 v[166:167], v[60:61], v[24:25] op_sel:[0,1]
	v_pk_mul_f32 v[168:169], v[62:63], v[24:25] op_sel_hi:[1,0]
	v_pk_mul_f32 v[170:171], v[62:63], v[24:25] op_sel:[0,1]
	v_pk_fma_f32 v[164:165], v[68:69], v[72:73], v[164:165] op_sel_hi:[1,0,1]
	v_pk_fma_f32 v[166:167], v[68:69], v[72:73], v[166:167] op_sel:[0,1,0]
	v_pk_fma_f32 v[168:169], v[70:71], v[72:73], v[168:169] op_sel_hi:[1,0,1]
	v_pk_fma_f32 v[170:171], v[70:71], v[72:73], v[170:171] op_sel:[0,1,0]
	v_pk_fma_f32 v[4:5], v[4:5], v[52:53], v[164:165]
	v_pk_fma_f32 v[12:13], v[12:13], v[52:53], v[166:167]
	v_pk_fma_f32 v[6:7], v[6:7], v[54:55], v[168:169]
	v_pk_fma_f32 v[14:15], v[14:15], v[54:55], v[170:171]
	v_pk_mul_f32 v[172:173], v[24:25], v[74:75] op_sel_hi:[1,0]
	v_pk_mul_f32 v[174:175], v[72:73], v[74:75] op_sel:[0,1]
	v_add_f32_e32 v26, v20, v21
	v_pk_add_f32 v[172:173], v[174:175], v[172:173]
	v_add_f32_e32 v27, v22, v23
	v_pk_fma_f32 v[180:181], v[172:173], v[128:129], v[26:27]
	s_waitcnt lgkmcnt(0)
	v_pk_mul_f32 v[16:17], v[2:3], v[78:79]
	v_pk_mul_f32 v[18:19], v[10:11], v[78:79]
	ds_read_b128 v[32:35], v130 offset:1024
	v_pk_fma_f32 v[16:17], v[0:1], v[76:77], v[16:17]
	v_pk_fma_f32 v[18:19], v[8:9], v[76:77], v[18:19]
	ds_read_b128 v[36:39], v130 offset:1040
	v_pk_fma_f32 v[16:17], v[4:5], v[80:81], v[16:17]
	v_pk_fma_f32 v[18:19], v[12:13], v[80:81], v[18:19]
	ds_read_b128 v[40:43], v130 offset:5120
	v_pk_fma_f32 v[16:17], v[6:7], v[82:83], v[16:17]
	v_pk_fma_f32 v[18:19], v[14:15], v[82:83], v[18:19]
	ds_read_b128 v[44:47], v130 offset:5136
	v_pk_mul_f32 v[20:21], v[2:3], v[92:93]
	v_add_f32_e32 v24, v16, v17
	ds_read_b128 v[56:59], v130 offset:13312
	v_add_f32_e32 v25, v18, v19
	v_pk_mul_f32 v[22:23], v[10:11], v[92:93]
	ds_read_b128 v[60:63], v130 offset:13328
	v_add_f32_dpp v24, v24, v24 quad_perm:[1,0,3,2] row_mask:0xf bank_mask:0xf bound_ctrl:1
	v_add_f32_dpp v25, v25, v25 quad_perm:[1,0,3,2] row_mask:0xf bank_mask:0xf bound_ctrl:1
	ds_read_b128 v[64:67], v130 offset:17408
	v_pk_fma_f32 v[20:21], v[0:1], v[90:91], v[20:21]
	v_add_f32_dpp v24, v24, v24 quad_perm:[2,3,0,1] row_mask:0xf bank_mask:0xf bound_ctrl:1
	ds_read_b128 v[68:71], v130 offset:17424
	v_add_f32_dpp v25, v25, v25 quad_perm:[2,3,0,1] row_mask:0xf bank_mask:0xf bound_ctrl:1
	v_pk_fma_f32 v[22:23], v[8:9], v[90:91], v[22:23]
	ds_read_b64 v[72:73], v131 offset:1024
	v_add_f32_dpp v24, v24, v24 row_half_mirror row_mask:0xf bank_mask:0xf bound_ctrl:1
	v_add_f32_dpp v25, v25, v25 row_half_mirror row_mask:0xf bank_mask:0xf bound_ctrl:1
	ds_read_b128 v[48:51], v130 offset:9216
	v_pk_fma_f32 v[20:21], v[4:5], v[94:95], v[20:21]
	v_pk_fma_f32 v[22:23], v[12:13], v[94:95], v[22:23]
	ds_read_b128 v[52:55], v130 offset:9232
	v_pk_fma_f32 v[20:21], v[6:7], v[96:97], v[20:21]
	v_pk_fma_f32 v[22:23], v[14:15], v[96:97], v[22:23]
	ds_read_b64 v[74:75], v85 offset:64
	v_pk_mul_f32 v[164:165], v[112:113], v[24:25] op_sel_hi:[1,0]
	v_pk_mul_f32 v[166:167], v[112:113], v[24:25] op_sel:[0,1]
	v_pk_mul_f32 v[168:169], v[114:115], v[24:25] op_sel_hi:[1,0]
	v_pk_mul_f32 v[170:171], v[114:115], v[24:25] op_sel:[0,1]
	v_pk_fma_f32 v[164:165], v[120:121], v[106:107], v[164:165] op_sel_hi:[1,0,1]
	v_pk_fma_f32 v[166:167], v[120:121], v[106:107], v[166:167] op_sel:[0,1,0]
	v_pk_fma_f32 v[168:169], v[122:123], v[106:107], v[168:169] op_sel_hi:[1,0,1]
	v_pk_fma_f32 v[170:171], v[122:123], v[106:107], v[170:171] op_sel:[0,1,0]
	v_pk_fma_f32 v[0:1], v[0:1], v[98:99], v[164:165]
	v_pk_fma_f32 v[8:9], v[8:9], v[98:99], v[166:167]
	v_pk_fma_f32 v[2:3], v[2:3], v[100:101], v[168:169]
	v_pk_fma_f32 v[10:11], v[10:11], v[100:101], v[170:171]
	v_pk_mul_f32 v[164:165], v[116:117], v[24:25] op_sel_hi:[1,0]
	v_pk_mul_f32 v[166:167], v[116:117], v[24:25] op_sel:[0,1]
	v_pk_mul_f32 v[168:169], v[118:119], v[24:25] op_sel_hi:[1,0]
	v_pk_mul_f32 v[170:171], v[118:119], v[24:25] op_sel:[0,1]
	v_pk_fma_f32 v[164:165], v[124:125], v[106:107], v[164:165] op_sel_hi:[1,0,1]
	v_pk_fma_f32 v[166:167], v[124:125], v[106:107], v[166:167] op_sel:[0,1,0]
	v_pk_fma_f32 v[168:169], v[126:127], v[106:107], v[168:169] op_sel_hi:[1,0,1]
	v_pk_fma_f32 v[170:171], v[126:127], v[106:107], v[170:171] op_sel:[0,1,0]
	v_pk_fma_f32 v[4:5], v[4:5], v[102:103], v[164:165]
	v_pk_fma_f32 v[12:13], v[12:13], v[102:103], v[166:167]
	v_pk_fma_f32 v[6:7], v[6:7], v[104:105], v[168:169]
	v_pk_fma_f32 v[14:15], v[14:15], v[104:105], v[170:171]
	v_pk_mul_f32 v[172:173], v[24:25], v[108:109] op_sel_hi:[1,0]
	v_pk_mul_f32 v[174:175], v[106:107], v[108:109] op_sel:[0,1]
	v_add_f32_e32 v26, v20, v21
	v_pk_add_f32 v[172:173], v[174:175], v[172:173]
	v_add_f32_e32 v27, v22, v23
	v_pk_fma_f32 v[182:183], v[172:173], v[128:129], v[26:27]
	v_cndmask_b32_e64 v140, v180, v176, s[44:45]
	v_cndmask_b32_e64 v141, v176, v180, s[44:45]
	v_cndmask_b32_e64 v142, v181, v177, s[44:45]
	v_cndmask_b32_e64 v143, v177, v181, s[44:45]
	v_cndmask_b32_e64 v144, v182, v178, s[44:45]
	v_cndmask_b32_e64 v145, v178, v182, s[44:45]
	v_cndmask_b32_e64 v146, v183, v179, s[44:45]
	v_cndmask_b32_e64 v147, v179, v183, s[44:45]
	v_add_f32_dpp v176, v141, v140 row_half_mirror row_mask:0xf bank_mask:0xf bound_ctrl:1
	v_add_f32_dpp v177, v143, v142 row_half_mirror row_mask:0xf bank_mask:0xf bound_ctrl:1
	v_add_f32_dpp v178, v145, v144 row_half_mirror row_mask:0xf bank_mask:0xf bound_ctrl:1
	v_add_f32_dpp v179, v147, v146 row_half_mirror row_mask:0xf bank_mask:0xf bound_ctrl:1
	v_cndmask_b32_e64 v140, v178, v176, s[46:47]
	v_cndmask_b32_e64 v141, v176, v178, s[46:47]
	v_cndmask_b32_e64 v142, v179, v177, s[46:47]
	v_cndmask_b32_e64 v143, v177, v179, s[46:47]
	v_add_u32_e32 v130, 0x400, v130
	v_add_f32_dpp v176, v141, v140 quad_perm:[2,3,0,1] row_mask:0xf bank_mask:0xf bound_ctrl:1
	v_add_u32_e32 v131, 0x400, v131
	v_add_f32_dpp v177, v143, v142 quad_perm:[2,3,0,1] row_mask:0xf bank_mask:0xf bound_ctrl:1
	v_add_u32_e32 v85, 64, v85
	v_cndmask_b32_e64 v140, v177, v176, s[48:49]
	v_cndmask_b32_e64 v141, v176, v177, s[48:49]
	s_add_i32 s0, s0, -1
	s_cmp_lg_u32 s0, 0
	v_add_f32_dpp v142, v141, v140 quad_perm:[1,0,3,2] row_mask:0xf bank_mask:0xf bound_ctrl:1
	s_nop 0
	ds_write_b32 v86, v142
	v_add_u32_e32 v86, 0x400, v86
	s_cbranch_scc1 .Lscan_q4
	s_xor_b32 s1, s1, 0x8200
	s_add_i32 s2, s2, -1
	s_waitcnt lgkmcnt(0)
	s_barrier
	s_cmp_lg_u32 s2, 0
	s_cbranch_scc1 .Lscan_chunk
	s_branch .LBB0_627
